# tile-start vmcnt(0) dropped in out-proj and FFN-out (first-iteration waits already cover the LDS fills); otherwise as v10
# speedup vs baseline: 1.0042x; 1.0042x over previous
.LBB0_514:
	s_ashr_i32 s21, s20, 31
	s_lshl_b64 s[22:23], s[20:21], 19
	s_add_u32 s22, s10, s22
	s_addc_u32 s23, s11, s23
	s_and_b64 s[24:25], s[6:7], exec
	s_cselect_b32 s21, s23, s31
	s_cselect_b32 s27, s22, s30
	s_ashr_i32 s19, s18, 31
	s_lshl_b64 s[24:25], s[18:19], 19
	s_add_u32 s24, s3, s24
	s_addc_u32 s25, s46, s25
	s_and_b64 s[36:37], s[6:7], exec
	s_cselect_b32 s19, s25, s39
	s_cselect_b32 s33, s24, s38
	s_add_u32 s30, s30, 0x40080
	s_addc_u32 s31, s31, 0
	s_add_u32 s36, s38, 0x100
	s_addc_u32 s37, s39, 0
	s_mov_b32 s54, -2
	s_waitcnt lgkmcnt(0)
	ds_read_b128 v[82:85], v193
	ds_read_b128 v[86:89], v193 offset:1024
	ds_read_b128 v[98:101], v193 offset:2048
	ds_read_b128 v[102:105], v193 offset:3072
	ds_read_b128 v[146:149], v195
	ds_read_b128 v[150:153], v195 offset:1024
	ds_read_b128 v[154:157], v195 offset:2048
	ds_read_b128 v[158:161], v195 offset:3072
	s_add_u32 s38, s30, 0xfffc0080
	s_addc_u32 s39, s31, -1
	s_cmp_eq_u32 s54, 12
	s_cselect_b32 s45, s21, s39
	s_cselect_b32 s44, s27, s38
	s_cselect_b32 s39, s19, s37
	s_cselect_b32 s38, s33, s36
	v_lshl_add_u64 v[190:191], s[30:31], 0, v[180:181]
	s_add_i32 m0, s29, 0xc000
	ds_read_b128 v[162:165], v197
	ds_read_b128 v[166:169], v197 offset:1024
	ds_read_b128 v[198:201], v197 offset:2048
	ds_read_b128 v[202:205], v197 offset:3072
	ds_read_b128 v[206:209], v197 offset:4096
	ds_read_b128 v[212:215], v197 offset:5120
	ds_read_b128 v[216:219], v197 offset:6144
	ds_read_b128 v[220:223], v197 offset:7168
	global_load_lds_dwordx4 v[190:191], off
	v_lshl_add_u64 v[190:191], s[30:31], 0, v[182:183]
	s_add_i32 m0, s29, 0xe000
	s_nop 0
	global_load_lds_dwordx4 v[190:191], off
	s_waitcnt vmcnt(48)
	s_waitcnt lgkmcnt(0)
	s_barrier
	s_setprio 1
	s_waitcnt lgkmcnt(0)
	v_mfma_f32_16x16x32_bf16 v[142:145], v[82:85], v[162:165], 0
	v_mfma_f32_16x16x32_bf16 v[138:141], v[98:101], v[162:165], 0
	v_mfma_f32_16x16x32_bf16 v[126:129], v[82:85], v[198:201], 0
	v_mfma_f32_16x16x32_bf16 v[122:125], v[98:101], v[198:201], 0
	v_mfma_f32_16x16x32_bf16 v[110:113], v[82:85], v[206:209], 0
	v_mfma_f32_16x16x32_bf16 v[106:109], v[98:101], v[206:209], 0
	v_mfma_f32_16x16x32_bf16 v[78:81], v[82:85], v[216:219], 0
	v_mfma_f32_16x16x32_bf16 v[74:77], v[98:101], v[216:219], 0
	v_mfma_f32_16x16x32_bf16 v[142:145], v[86:89], v[166:169], v[142:145]
	v_mfma_f32_16x16x32_bf16 v[138:141], v[102:105], v[166:169], v[138:141]
	v_mfma_f32_16x16x32_bf16 v[126:129], v[86:89], v[202:205], v[126:129]
	v_mfma_f32_16x16x32_bf16 v[122:125], v[102:105], v[202:205], v[122:125]
	v_mfma_f32_16x16x32_bf16 v[110:113], v[86:89], v[212:215], v[110:113]
	v_mfma_f32_16x16x32_bf16 v[106:109], v[102:105], v[212:215], v[106:109]
	v_mfma_f32_16x16x32_bf16 v[78:81], v[86:89], v[220:223], v[78:81]
	v_mfma_f32_16x16x32_bf16 v[74:77], v[102:105], v[220:223], v[74:77]
	s_setprio 0
	s_setprio 1
	v_mfma_f32_16x16x32_bf16 v[134:137], v[146:149], v[162:165], 0
	v_mfma_f32_16x16x32_bf16 v[130:133], v[154:157], v[162:165], 0
	v_mfma_f32_16x16x32_bf16 v[118:121], v[146:149], v[198:201], 0
	v_mfma_f32_16x16x32_bf16 v[114:117], v[154:157], v[198:201], 0
	v_mfma_f32_16x16x32_bf16 v[94:97], v[146:149], v[206:209], 0
	v_mfma_f32_16x16x32_bf16 v[90:93], v[154:157], v[206:209], 0
	v_mfma_f32_16x16x32_bf16 v[70:73], v[146:149], v[216:219], 0
	v_mfma_f32_16x16x32_bf16 v[66:69], v[154:157], v[216:219], 0
	v_mfma_f32_16x16x32_bf16 v[134:137], v[150:153], v[166:169], v[134:137]
	v_mfma_f32_16x16x32_bf16 v[130:133], v[158:161], v[166:169], v[130:133]
	v_mfma_f32_16x16x32_bf16 v[118:121], v[150:153], v[202:205], v[118:121]
	v_mfma_f32_16x16x32_bf16 v[114:117], v[158:161], v[202:205], v[114:117]
	v_mfma_f32_16x16x32_bf16 v[94:97], v[150:153], v[212:215], v[94:97]
	v_mfma_f32_16x16x32_bf16 v[90:93], v[158:161], v[212:215], v[90:93]
	v_mfma_f32_16x16x32_bf16 v[70:73], v[150:153], v[220:223], v[70:73]
	v_mfma_f32_16x16x32_bf16 v[66:69], v[158:161], v[220:223], v[66:69]
	s_setprio 0
	s_barrier
	s_add_i32 s42, s55, s47
	v_lshl_add_u64 v[190:191], s[38:39], 0, v[174:175]
	s_mov_b32 m0, s42
	ds_read_b128 v[162:165], v197 offset:16384
	ds_read_b128 v[166:169], v197 offset:17408
	ds_read_b128 v[198:201], v197 offset:18432
	ds_read_b128 v[202:205], v197 offset:19456
	ds_read_b128 v[206:209], v197 offset:20480
	ds_read_b128 v[212:215], v197 offset:21504
	ds_read_b128 v[216:219], v197 offset:22528
	ds_read_b128 v[220:223], v197 offset:23552
	global_load_lds_dwordx4 v[190:191], off
	s_add_i32 m0, s42, 0x2000
	s_add_u32 s42, s38, 0x40000
	v_lshl_add_u64 v[224:225], s[38:39], 0, v[178:179]
	s_addc_u32 s43, s39, 0
	s_add_i32 s57, s56, s47
	global_load_lds_dwordx4 v[224:225], off
	v_lshl_add_u64 v[226:227], s[42:43], 0, v[174:175]
	s_mov_b32 m0, s57
	v_lshl_add_u64 v[228:229], s[44:45], 0, v[176:177]
	global_load_lds_dwordx4 v[226:227], off
	v_lshl_add_u64 v[226:227], s[42:43], 0, v[178:179]
	s_add_i32 m0, s57, 0x2000
	s_nop 0
	global_load_lds_dwordx4 v[226:227], off
	v_lshl_add_u64 v[226:227], s[44:45], 0, v[172:173]
	s_mov_b32 m0, s29
	s_nop 0
	global_load_lds_dwordx4 v[226:227], off
	s_mov_b32 m0, s48
	s_nop 0
	global_load_lds_dwordx4 v[228:229], off
	s_waitcnt vmcnt(48)
	s_waitcnt lgkmcnt(0)
	s_barrier
	s_setprio 1
	s_waitcnt lgkmcnt(0)
	v_mfma_f32_16x16x32_bf16 v[62:65], v[82:85], v[162:165], 0
	v_mfma_f32_16x16x32_bf16 v[58:61], v[98:101], v[162:165], 0
	v_mfma_f32_16x16x32_bf16 v[46:49], v[82:85], v[198:201], 0
	v_mfma_f32_16x16x32_bf16 v[42:45], v[98:101], v[198:201], 0
	v_mfma_f32_16x16x32_bf16 v[30:33], v[82:85], v[206:209], 0
	v_mfma_f32_16x16x32_bf16 v[26:29], v[98:101], v[206:209], 0
	v_mfma_f32_16x16x32_bf16 v[14:17], v[82:85], v[216:219], 0
	v_mfma_f32_16x16x32_bf16 v[10:13], v[98:101], v[216:219], 0
	v_mfma_f32_16x16x32_bf16 v[62:65], v[86:89], v[166:169], v[62:65]
	v_mfma_f32_16x16x32_bf16 v[58:61], v[102:105], v[166:169], v[58:61]
	v_mfma_f32_16x16x32_bf16 v[46:49], v[86:89], v[202:205], v[46:49]
	v_mfma_f32_16x16x32_bf16 v[42:45], v[102:105], v[202:205], v[42:45]
	v_mfma_f32_16x16x32_bf16 v[30:33], v[86:89], v[212:215], v[30:33]
	v_mfma_f32_16x16x32_bf16 v[26:29], v[102:105], v[212:215], v[26:29]
	v_mfma_f32_16x16x32_bf16 v[14:17], v[86:89], v[220:223], v[14:17]
	v_mfma_f32_16x16x32_bf16 v[10:13], v[102:105], v[220:223], v[10:13]
	s_setprio 0
	s_setprio 1
	v_mfma_f32_16x16x32_bf16 v[54:57], v[146:149], v[162:165], 0
	v_mfma_f32_16x16x32_bf16 v[50:53], v[154:157], v[162:165], 0
	v_mfma_f32_16x16x32_bf16 v[38:41], v[146:149], v[198:201], 0
	v_mfma_f32_16x16x32_bf16 v[34:37], v[154:157], v[198:201], 0
	v_mfma_f32_16x16x32_bf16 v[22:25], v[146:149], v[206:209], 0
	v_mfma_f32_16x16x32_bf16 v[18:21], v[154:157], v[206:209], 0
	v_mfma_f32_16x16x32_bf16 v[6:9], v[146:149], v[216:219], 0
	v_mfma_f32_16x16x32_bf16 v[2:5], v[154:157], v[216:219], 0
	v_mfma_f32_16x16x32_bf16 v[54:57], v[150:153], v[166:169], v[54:57]
	v_mfma_f32_16x16x32_bf16 v[50:53], v[158:161], v[166:169], v[50:53]
	v_mfma_f32_16x16x32_bf16 v[38:41], v[150:153], v[202:205], v[38:41]
	v_mfma_f32_16x16x32_bf16 v[34:37], v[158:161], v[202:205], v[34:37]
	v_mfma_f32_16x16x32_bf16 v[22:25], v[150:153], v[212:215], v[22:25]
	v_mfma_f32_16x16x32_bf16 v[18:21], v[158:161], v[212:215], v[18:21]
	v_mfma_f32_16x16x32_bf16 v[6:9], v[150:153], v[220:223], v[6:9]
	v_mfma_f32_16x16x32_bf16 v[2:5], v[158:161], v[220:223], v[2:5]
	s_setprio 0
	s_barrier
	s_add_i32 s57, 0, 0x18000
	s_add_i32 s58, 0, 0x1c000
	v_add_u32_e32 v102, s57, v171
	v_add_u32_e32 v158, s58, v171
	ds_read_b128 v[82:85], v102
	ds_read_b128 v[86:89], v102 offset:1024
	ds_read_b128 v[98:101], v102 offset:2048
	ds_read_b128 v[102:105], v102 offset:3072
	ds_read_b128 v[146:149], v158
	ds_read_b128 v[150:153], v158 offset:1024
	ds_read_b128 v[154:157], v158 offset:2048
	ds_read_b128 v[158:161], v158 offset:3072
	s_add_u32 s42, s44, 0x40000
	s_addc_u32 s43, s45, 0
	s_mov_b32 m0, s49
	v_lshl_add_u64 v[230:231], s[42:43], 0, v[172:173]
	ds_read_b128 v[162:165], v197 offset:32768
	ds_read_b128 v[166:169], v197 offset:33792
	ds_read_b128 v[198:201], v197 offset:34816
	ds_read_b128 v[202:205], v197 offset:35840
	ds_read_b128 v[206:209], v197 offset:36864
	ds_read_b128 v[212:215], v197 offset:37888
	ds_read_b128 v[216:219], v197 offset:38912
	ds_read_b128 v[220:223], v197 offset:39936
	global_load_lds_dwordx4 v[230:231], off
	v_lshl_add_u64 v[230:231], s[42:43], 0, v[176:177]
	s_mov_b32 m0, s50
	s_nop 0
	global_load_lds_dwordx4 v[230:231], off
	s_waitcnt vmcnt(8)
	s_waitcnt lgkmcnt(0)
	s_barrier
	s_setprio 1
	s_waitcnt lgkmcnt(0)
	v_mfma_f32_16x16x32_bf16 v[142:145], v[82:85], v[162:165], v[142:145]
	v_mfma_f32_16x16x32_bf16 v[138:141], v[98:101], v[162:165], v[138:141]
	v_mfma_f32_16x16x32_bf16 v[126:129], v[82:85], v[198:201], v[126:129]
	v_mfma_f32_16x16x32_bf16 v[122:125], v[98:101], v[198:201], v[122:125]
	v_mfma_f32_16x16x32_bf16 v[110:113], v[82:85], v[206:209], v[110:113]
	v_mfma_f32_16x16x32_bf16 v[106:109], v[98:101], v[206:209], v[106:109]
	v_mfma_f32_16x16x32_bf16 v[78:81], v[82:85], v[216:219], v[78:81]
	v_mfma_f32_16x16x32_bf16 v[74:77], v[98:101], v[216:219], v[74:77]
	v_mfma_f32_16x16x32_bf16 v[142:145], v[86:89], v[166:169], v[142:145]
	v_mfma_f32_16x16x32_bf16 v[138:141], v[102:105], v[166:169], v[138:141]
	v_mfma_f32_16x16x32_bf16 v[126:129], v[86:89], v[202:205], v[126:129]
	v_mfma_f32_16x16x32_bf16 v[122:125], v[102:105], v[202:205], v[122:125]
	v_mfma_f32_16x16x32_bf16 v[110:113], v[86:89], v[212:215], v[110:113]
	v_mfma_f32_16x16x32_bf16 v[106:109], v[102:105], v[212:215], v[106:109]
	v_mfma_f32_16x16x32_bf16 v[78:81], v[86:89], v[220:223], v[78:81]
	v_mfma_f32_16x16x32_bf16 v[74:77], v[102:105], v[220:223], v[74:77]
	s_setprio 0
	s_setprio 1
	v_mfma_f32_16x16x32_bf16 v[134:137], v[146:149], v[162:165], v[134:137]
	v_mfma_f32_16x16x32_bf16 v[130:133], v[154:157], v[162:165], v[130:133]
	v_mfma_f32_16x16x32_bf16 v[118:121], v[146:149], v[198:201], v[118:121]
	v_mfma_f32_16x16x32_bf16 v[114:117], v[154:157], v[198:201], v[114:117]
	v_mfma_f32_16x16x32_bf16 v[94:97], v[146:149], v[206:209], v[94:97]
	v_mfma_f32_16x16x32_bf16 v[90:93], v[154:157], v[206:209], v[90:93]
	v_mfma_f32_16x16x32_bf16 v[70:73], v[146:149], v[216:219], v[70:73]
	v_mfma_f32_16x16x32_bf16 v[66:69], v[154:157], v[216:219], v[66:69]
	v_mfma_f32_16x16x32_bf16 v[134:137], v[150:153], v[166:169], v[134:137]
	v_mfma_f32_16x16x32_bf16 v[130:133], v[158:161], v[166:169], v[130:133]
	v_mfma_f32_16x16x32_bf16 v[118:121], v[150:153], v[202:205], v[118:121]
	v_mfma_f32_16x16x32_bf16 v[114:117], v[158:161], v[202:205], v[114:117]
	v_mfma_f32_16x16x32_bf16 v[94:97], v[150:153], v[212:215], v[94:97]
	v_mfma_f32_16x16x32_bf16 v[90:93], v[158:161], v[212:215], v[90:93]
	v_mfma_f32_16x16x32_bf16 v[70:73], v[150:153], v[220:223], v[70:73]
	v_mfma_f32_16x16x32_bf16 v[66:69], v[158:161], v[220:223], v[66:69]
	s_setprio 0
	s_barrier
	s_add_i32 s42, s57, s47
	v_lshl_add_u64 v[190:191], v[190:191], 0, s[14:15]
	s_mov_b32 m0, s42
	ds_read_b128 v[162:165], v197 offset:49152
	ds_read_b128 v[166:169], v197 offset:50176
	ds_read_b128 v[198:201], v197 offset:51200
	ds_read_b128 v[202:205], v197 offset:52224
	ds_read_b128 v[206:209], v197 offset:53248
	ds_read_b128 v[212:215], v197 offset:54272
	ds_read_b128 v[216:219], v197 offset:55296
	ds_read_b128 v[220:223], v197 offset:56320
	global_load_lds_dwordx4 v[190:191], off
	s_add_i32 m0, s42, 0x2000
	s_add_u32 s38, s38, 0x40080
	v_lshl_add_u64 v[190:191], v[224:225], 0, s[14:15]
	s_addc_u32 s39, s39, 0
	s_add_i32 s42, s58, s47
	global_load_lds_dwordx4 v[190:191], off
	v_lshl_add_u64 v[190:191], s[38:39], 0, v[174:175]
	s_mov_b32 m0, s42
	s_nop 0
	global_load_lds_dwordx4 v[190:191], off
	v_lshl_add_u64 v[190:191], s[38:39], 0, v[178:179]
	s_add_i32 m0, s42, 0x2000
	s_nop 0
	global_load_lds_dwordx4 v[190:191], off
	v_lshl_add_u64 v[190:191], v[226:227], 0, s[14:15]
	s_mov_b32 m0, s52
	s_nop 0
	global_load_lds_dwordx4 v[190:191], off
	v_lshl_add_u64 v[190:191], v[228:229], 0, s[14:15]
	s_mov_b32 m0, s53
	s_nop 0
	global_load_lds_dwordx4 v[190:191], off
	s_waitcnt vmcnt(8)
	s_waitcnt lgkmcnt(0)
	s_barrier
	s_setprio 1
	s_waitcnt lgkmcnt(0)
	v_mfma_f32_16x16x32_bf16 v[62:65], v[82:85], v[162:165], v[62:65]
	v_mfma_f32_16x16x32_bf16 v[58:61], v[98:101], v[162:165], v[58:61]
	v_mfma_f32_16x16x32_bf16 v[46:49], v[82:85], v[198:201], v[46:49]
	v_mfma_f32_16x16x32_bf16 v[42:45], v[98:101], v[198:201], v[42:45]
	v_mfma_f32_16x16x32_bf16 v[30:33], v[82:85], v[206:209], v[30:33]
	v_mfma_f32_16x16x32_bf16 v[26:29], v[98:101], v[206:209], v[26:29]
	v_mfma_f32_16x16x32_bf16 v[14:17], v[82:85], v[216:219], v[14:17]
	v_mfma_f32_16x16x32_bf16 v[10:13], v[98:101], v[216:219], v[10:13]
	v_mfma_f32_16x16x32_bf16 v[62:65], v[86:89], v[166:169], v[62:65]
	v_mfma_f32_16x16x32_bf16 v[58:61], v[102:105], v[166:169], v[58:61]
	v_mfma_f32_16x16x32_bf16 v[46:49], v[86:89], v[202:205], v[46:49]
	v_mfma_f32_16x16x32_bf16 v[42:45], v[102:105], v[202:205], v[42:45]
	v_mfma_f32_16x16x32_bf16 v[30:33], v[86:89], v[212:215], v[30:33]
	v_mfma_f32_16x16x32_bf16 v[26:29], v[102:105], v[212:215], v[26:29]
	v_mfma_f32_16x16x32_bf16 v[14:17], v[86:89], v[220:223], v[14:17]
	v_mfma_f32_16x16x32_bf16 v[10:13], v[102:105], v[220:223], v[10:13]
	s_setprio 0
	s_setprio 1
	v_mfma_f32_16x16x32_bf16 v[54:57], v[146:149], v[162:165], v[54:57]
	v_mfma_f32_16x16x32_bf16 v[50:53], v[154:157], v[162:165], v[50:53]
	v_mfma_f32_16x16x32_bf16 v[38:41], v[146:149], v[198:201], v[38:41]
	v_mfma_f32_16x16x32_bf16 v[34:37], v[154:157], v[198:201], v[34:37]
	v_mfma_f32_16x16x32_bf16 v[22:25], v[146:149], v[206:209], v[22:25]
	v_mfma_f32_16x16x32_bf16 v[18:21], v[154:157], v[206:209], v[18:21]
	v_mfma_f32_16x16x32_bf16 v[6:9], v[146:149], v[216:219], v[6:9]
	v_mfma_f32_16x16x32_bf16 v[2:5], v[154:157], v[216:219], v[2:5]
	v_mfma_f32_16x16x32_bf16 v[54:57], v[150:153], v[166:169], v[54:57]
	v_mfma_f32_16x16x32_bf16 v[50:53], v[158:161], v[166:169], v[50:53]
	v_mfma_f32_16x16x32_bf16 v[38:41], v[150:153], v[202:205], v[38:41]
	v_mfma_f32_16x16x32_bf16 v[34:37], v[158:161], v[202:205], v[34:37]
	v_mfma_f32_16x16x32_bf16 v[22:25], v[150:153], v[212:215], v[22:25]
	v_mfma_f32_16x16x32_bf16 v[18:21], v[158:161], v[212:215], v[18:21]
	v_mfma_f32_16x16x32_bf16 v[6:9], v[150:153], v[220:223], v[6:9]
	v_mfma_f32_16x16x32_bf16 v[2:5], v[158:161], v[220:223], v[2:5]
	s_setprio 0
	s_barrier
	s_add_i32 s54, s54, 2
	s_add_u32 s30, s30, 0x100
	s_addc_u32 s31, s31, 0
	s_add_u32 s36, s36, 0x100
	s_addc_u32 s37, s37, 0

.LBB0_695:
	s_add_i32 s36, s33, -2
	s_add_u32 s37, s52, 0x100
	s_addc_u32 s39, s53, 0
	s_mov_b32 s47, 0
	ds_read_b128 v[130:133], v213
	ds_read_b128 v[134:137], v213 offset:1024
	ds_read_b128 v[138:141], v213 offset:2048
	ds_read_b128 v[142:145], v213 offset:3072
	ds_read_b128 v[146:149], v214
	ds_read_b128 v[150:153], v214 offset:1024
	ds_read_b128 v[154:157], v214 offset:2048
	ds_read_b128 v[158:161], v214 offset:3072
	s_add_i32 s49, s47, 2
	s_add_u32 s52, s50, 0x100
	s_addc_u32 s53, s51, 0
	s_cmp_eq_u32 s36, s47
	s_cselect_b32 s57, s43, s53
	s_cselect_b32 s56, s42, s52
	s_cselect_b32 s55, s45, s39
	s_cselect_b32 s54, s44, s37
	v_lshl_add_u64 v[224:225], s[50:51], 0, v[174:175]
	s_add_i32 m0, s60, 0xc000
	ds_read_b128 v[180:183], v215
	ds_read_b128 v[184:187], v215 offset:1024
	ds_read_b128 v[188:191], v215 offset:2048
	ds_read_b128 v[192:195], v215 offset:3072
	ds_read_b128 v[196:199], v215 offset:4096
	ds_read_b128 v[200:203], v215 offset:5120
	ds_read_b128 v[204:207], v215 offset:6144
	ds_read_b128 v[220:223], v215 offset:7168
	global_load_lds_dwordx4 v[224:225], off
	v_lshl_add_u64 v[224:225], s[50:51], 0, v[176:177]
	s_add_i32 m0, s60, 0xe000
	s_nop 0
	global_load_lds_dwordx4 v[224:225], off
	s_waitcnt vmcnt(38)
	s_waitcnt lgkmcnt(0)
	s_barrier
	s_setprio 1
	s_waitcnt lgkmcnt(0)
	v_mfma_f32_16x16x32_bf16 v[126:129], v[130:133], v[180:183], 0
	v_mfma_f32_16x16x32_bf16 v[122:125], v[138:141], v[180:183], 0
	v_mfma_f32_16x16x32_bf16 v[118:121], v[130:133], v[188:191], 0
	v_mfma_f32_16x16x32_bf16 v[114:117], v[138:141], v[188:191], 0
	v_mfma_f32_16x16x32_bf16 v[102:105], v[130:133], v[196:199], 0
	v_mfma_f32_16x16x32_bf16 v[98:101], v[138:141], v[196:199], 0
	v_mfma_f32_16x16x32_bf16 v[86:89], v[130:133], v[204:207], 0
	v_mfma_f32_16x16x32_bf16 v[82:85], v[138:141], v[204:207], 0
	v_mfma_f32_16x16x32_bf16 v[126:129], v[134:137], v[184:187], v[126:129]
	v_mfma_f32_16x16x32_bf16 v[122:125], v[142:145], v[184:187], v[122:125]
	v_mfma_f32_16x16x32_bf16 v[118:121], v[134:137], v[192:195], v[118:121]
	v_mfma_f32_16x16x32_bf16 v[114:117], v[142:145], v[192:195], v[114:117]
	v_mfma_f32_16x16x32_bf16 v[102:105], v[134:137], v[200:203], v[102:105]
	v_mfma_f32_16x16x32_bf16 v[98:101], v[142:145], v[200:203], v[98:101]
	v_mfma_f32_16x16x32_bf16 v[86:89], v[134:137], v[220:223], v[86:89]
	v_mfma_f32_16x16x32_bf16 v[82:85], v[142:145], v[220:223], v[82:85]
	s_setprio 0
	s_setprio 1
	v_mfma_f32_16x16x32_bf16 v[110:113], v[146:149], v[180:183], 0
	v_mfma_f32_16x16x32_bf16 v[106:109], v[154:157], v[180:183], 0
	v_mfma_f32_16x16x32_bf16 v[94:97], v[146:149], v[188:191], 0
	v_mfma_f32_16x16x32_bf16 v[90:93], v[154:157], v[188:191], 0
	v_mfma_f32_16x16x32_bf16 v[78:81], v[146:149], v[196:199], 0
	v_mfma_f32_16x16x32_bf16 v[74:77], v[154:157], v[196:199], 0
	v_mfma_f32_16x16x32_bf16 v[70:73], v[146:149], v[204:207], 0
	v_mfma_f32_16x16x32_bf16 v[66:69], v[154:157], v[204:207], 0
	v_mfma_f32_16x16x32_bf16 v[110:113], v[150:153], v[184:187], v[110:113]
	v_mfma_f32_16x16x32_bf16 v[106:109], v[158:161], v[184:187], v[106:109]
	v_mfma_f32_16x16x32_bf16 v[94:97], v[150:153], v[192:195], v[94:97]
	v_mfma_f32_16x16x32_bf16 v[90:93], v[158:161], v[192:195], v[90:93]
	v_mfma_f32_16x16x32_bf16 v[78:81], v[150:153], v[200:203], v[78:81]
	v_mfma_f32_16x16x32_bf16 v[74:77], v[158:161], v[200:203], v[74:77]
	v_mfma_f32_16x16x32_bf16 v[70:73], v[150:153], v[220:223], v[70:73]
	v_mfma_f32_16x16x32_bf16 v[66:69], v[158:161], v[220:223], v[66:69]
	s_setprio 0
	s_barrier
	s_add_i32 s47, s67, s59
	v_lshl_add_u64 v[224:225], s[54:55], 0, v[164:165]
	s_mov_b32 m0, s47
	ds_read_b128 v[180:183], v215 offset:16384
	ds_read_b128 v[184:187], v215 offset:17408
	ds_read_b128 v[188:191], v215 offset:18432
	ds_read_b128 v[192:195], v215 offset:19456
	ds_read_b128 v[196:199], v215 offset:20480
	ds_read_b128 v[200:203], v215 offset:21504
	ds_read_b128 v[204:207], v215 offset:22528
	ds_read_b128 v[220:223], v215 offset:23552
	global_load_lds_dwordx4 v[224:225], off
	s_add_i32 m0, s47, 0x2000
	s_add_u32 s50, s54, 0xb0000
	v_lshl_add_u64 v[226:227], s[54:55], 0, v[168:169]
	s_addc_u32 s51, s55, 0
	s_add_i32 s47, s68, s59
	global_load_lds_dwordx4 v[226:227], off
	v_lshl_add_u64 v[228:229], s[50:51], 0, v[164:165]
	s_mov_b32 m0, s47
	v_lshl_add_u64 v[230:231], s[56:57], 0, v[166:167]
	global_load_lds_dwordx4 v[228:229], off
	v_lshl_add_u64 v[228:229], s[50:51], 0, v[168:169]
	s_add_i32 m0, s47, 0x2000
	s_nop 0
	global_load_lds_dwordx4 v[228:229], off
	v_lshl_add_u64 v[228:229], s[56:57], 0, v[162:163]
	s_mov_b32 m0, s60
	s_nop 0
	global_load_lds_dwordx4 v[228:229], off
	s_mov_b32 m0, s61
	s_nop 0
	global_load_lds_dwordx4 v[230:231], off
	s_waitcnt vmcnt(38)
	s_waitcnt lgkmcnt(0)
	s_barrier
	s_setprio 1
	s_waitcnt lgkmcnt(0)
	v_mfma_f32_16x16x32_bf16 v[62:65], v[130:133], v[180:183], 0
	v_mfma_f32_16x16x32_bf16 v[58:61], v[138:141], v[180:183], 0
	v_mfma_f32_16x16x32_bf16 v[54:57], v[130:133], v[188:191], 0
	v_mfma_f32_16x16x32_bf16 v[50:53], v[138:141], v[188:191], 0
	v_mfma_f32_16x16x32_bf16 v[38:41], v[130:133], v[196:199], 0
	v_mfma_f32_16x16x32_bf16 v[34:37], v[138:141], v[196:199], 0
	v_mfma_f32_16x16x32_bf16 v[22:25], v[130:133], v[204:207], 0
	v_mfma_f32_16x16x32_bf16 v[18:21], v[138:141], v[204:207], 0
	v_mfma_f32_16x16x32_bf16 v[62:65], v[134:137], v[184:187], v[62:65]
	v_mfma_f32_16x16x32_bf16 v[58:61], v[142:145], v[184:187], v[58:61]
	v_mfma_f32_16x16x32_bf16 v[54:57], v[134:137], v[192:195], v[54:57]
	v_mfma_f32_16x16x32_bf16 v[50:53], v[142:145], v[192:195], v[50:53]
	v_mfma_f32_16x16x32_bf16 v[38:41], v[134:137], v[200:203], v[38:41]
	v_mfma_f32_16x16x32_bf16 v[34:37], v[142:145], v[200:203], v[34:37]
	v_mfma_f32_16x16x32_bf16 v[22:25], v[134:137], v[220:223], v[22:25]
	v_mfma_f32_16x16x32_bf16 v[18:21], v[142:145], v[220:223], v[18:21]
	s_setprio 0
	s_setprio 1
	v_mfma_f32_16x16x32_bf16 v[46:49], v[146:149], v[180:183], 0
	v_mfma_f32_16x16x32_bf16 v[42:45], v[154:157], v[180:183], 0
	v_mfma_f32_16x16x32_bf16 v[30:33], v[146:149], v[188:191], 0
	v_mfma_f32_16x16x32_bf16 v[26:29], v[154:157], v[188:191], 0
	v_mfma_f32_16x16x32_bf16 v[14:17], v[146:149], v[196:199], 0
	v_mfma_f32_16x16x32_bf16 v[10:13], v[154:157], v[196:199], 0
	v_mfma_f32_16x16x32_bf16 v[6:9], v[146:149], v[204:207], 0
	v_mfma_f32_16x16x32_bf16 v[2:5], v[154:157], v[204:207], 0
	v_mfma_f32_16x16x32_bf16 v[46:49], v[150:153], v[184:187], v[46:49]
	v_mfma_f32_16x16x32_bf16 v[42:45], v[158:161], v[184:187], v[42:45]
	v_mfma_f32_16x16x32_bf16 v[30:33], v[150:153], v[192:195], v[30:33]
	v_mfma_f32_16x16x32_bf16 v[26:29], v[158:161], v[192:195], v[26:29]
	v_mfma_f32_16x16x32_bf16 v[14:17], v[150:153], v[200:203], v[14:17]
	v_mfma_f32_16x16x32_bf16 v[10:13], v[158:161], v[200:203], v[10:13]
	v_mfma_f32_16x16x32_bf16 v[6:9], v[150:153], v[220:223], v[6:9]
	v_mfma_f32_16x16x32_bf16 v[2:5], v[158:161], v[220:223], v[2:5]
	s_setprio 0
	s_barrier
	s_add_i32 s47, 0, 0x18000
	s_add_i32 s84, 0, 0x1c000
	v_add_u32_e32 v142, s47, v208
	v_add_u32_e32 v158, s84, v208
	ds_read_b128 v[130:133], v142
	ds_read_b128 v[134:137], v142 offset:1024
	ds_read_b128 v[138:141], v142 offset:2048
	ds_read_b128 v[142:145], v142 offset:3072
	ds_read_b128 v[146:149], v158
	ds_read_b128 v[150:153], v158 offset:1024
	ds_read_b128 v[154:157], v158 offset:2048
	ds_read_b128 v[158:161], v158 offset:3072
	s_add_u32 s50, s56, 0xb0000
	s_addc_u32 s51, s57, 0
	s_mov_b32 m0, s62
	v_lshl_add_u64 v[232:233], s[50:51], 0, v[162:163]
	ds_read_b128 v[180:183], v215 offset:32768
	ds_read_b128 v[184:187], v215 offset:33792
	ds_read_b128 v[188:191], v215 offset:34816
	ds_read_b128 v[192:195], v215 offset:35840
	ds_read_b128 v[196:199], v215 offset:36864
	ds_read_b128 v[200:203], v215 offset:37888
	ds_read_b128 v[204:207], v215 offset:38912
	ds_read_b128 v[220:223], v215 offset:39936
	global_load_lds_dwordx4 v[232:233], off
	v_lshl_add_u64 v[232:233], s[50:51], 0, v[166:167]
	s_mov_b32 m0, s63
	s_nop 0
	global_load_lds_dwordx4 v[232:233], off
	s_waitcnt vmcnt(8)
	s_waitcnt lgkmcnt(0)
	s_barrier
	s_setprio 1
	s_waitcnt lgkmcnt(0)
	v_mfma_f32_16x16x32_bf16 v[126:129], v[130:133], v[180:183], v[126:129]
	v_mfma_f32_16x16x32_bf16 v[122:125], v[138:141], v[180:183], v[122:125]
	v_mfma_f32_16x16x32_bf16 v[118:121], v[130:133], v[188:191], v[118:121]
	v_mfma_f32_16x16x32_bf16 v[114:117], v[138:141], v[188:191], v[114:117]
	v_mfma_f32_16x16x32_bf16 v[102:105], v[130:133], v[196:199], v[102:105]
	v_mfma_f32_16x16x32_bf16 v[98:101], v[138:141], v[196:199], v[98:101]
	v_mfma_f32_16x16x32_bf16 v[86:89], v[130:133], v[204:207], v[86:89]
	v_mfma_f32_16x16x32_bf16 v[82:85], v[138:141], v[204:207], v[82:85]
	v_mfma_f32_16x16x32_bf16 v[126:129], v[134:137], v[184:187], v[126:129]
	v_mfma_f32_16x16x32_bf16 v[122:125], v[142:145], v[184:187], v[122:125]
	v_mfma_f32_16x16x32_bf16 v[118:121], v[134:137], v[192:195], v[118:121]
	v_mfma_f32_16x16x32_bf16 v[114:117], v[142:145], v[192:195], v[114:117]
	v_mfma_f32_16x16x32_bf16 v[102:105], v[134:137], v[200:203], v[102:105]
	v_mfma_f32_16x16x32_bf16 v[98:101], v[142:145], v[200:203], v[98:101]
	v_mfma_f32_16x16x32_bf16 v[86:89], v[134:137], v[220:223], v[86:89]
	v_mfma_f32_16x16x32_bf16 v[82:85], v[142:145], v[220:223], v[82:85]
	s_setprio 0
	s_setprio 1
	v_mfma_f32_16x16x32_bf16 v[110:113], v[146:149], v[180:183], v[110:113]
	v_mfma_f32_16x16x32_bf16 v[106:109], v[154:157], v[180:183], v[106:109]
	v_mfma_f32_16x16x32_bf16 v[94:97], v[146:149], v[188:191], v[94:97]
	v_mfma_f32_16x16x32_bf16 v[90:93], v[154:157], v[188:191], v[90:93]
	v_mfma_f32_16x16x32_bf16 v[78:81], v[146:149], v[196:199], v[78:81]
	v_mfma_f32_16x16x32_bf16 v[74:77], v[154:157], v[196:199], v[74:77]
	v_mfma_f32_16x16x32_bf16 v[70:73], v[146:149], v[204:207], v[70:73]
	v_mfma_f32_16x16x32_bf16 v[66:69], v[154:157], v[204:207], v[66:69]
	v_mfma_f32_16x16x32_bf16 v[110:113], v[150:153], v[184:187], v[110:113]
	v_mfma_f32_16x16x32_bf16 v[106:109], v[158:161], v[184:187], v[106:109]
	v_mfma_f32_16x16x32_bf16 v[94:97], v[150:153], v[192:195], v[94:97]
	v_mfma_f32_16x16x32_bf16 v[90:93], v[158:161], v[192:195], v[90:93]
	v_mfma_f32_16x16x32_bf16 v[78:81], v[150:153], v[200:203], v[78:81]
	v_mfma_f32_16x16x32_bf16 v[74:77], v[158:161], v[200:203], v[74:77]
	v_mfma_f32_16x16x32_bf16 v[70:73], v[150:153], v[220:223], v[70:73]
	v_mfma_f32_16x16x32_bf16 v[66:69], v[158:161], v[220:223], v[66:69]
	s_setprio 0
	s_barrier
	s_add_i32 s47, s47, s59
	v_lshl_add_u64 v[224:225], v[224:225], 0, s[16:17]
	s_mov_b32 m0, s47
	ds_read_b128 v[180:183], v215 offset:49152
	ds_read_b128 v[184:187], v215 offset:50176
	ds_read_b128 v[188:191], v215 offset:51200
	ds_read_b128 v[192:195], v215 offset:52224
	ds_read_b128 v[196:199], v215 offset:53248
	ds_read_b128 v[200:203], v215 offset:54272
	ds_read_b128 v[204:207], v215 offset:55296
	ds_read_b128 v[220:223], v215 offset:56320
	global_load_lds_dwordx4 v[224:225], off
	s_add_i32 m0, s47, 0x2000
	s_add_u32 s50, s54, 0xb0080
	v_lshl_add_u64 v[224:225], v[226:227], 0, s[16:17]
	s_addc_u32 s51, s55, 0
	s_add_i32 s47, s84, s59
	global_load_lds_dwordx4 v[224:225], off
	v_lshl_add_u64 v[224:225], s[50:51], 0, v[164:165]
	s_mov_b32 m0, s47
	s_nop 0
	global_load_lds_dwordx4 v[224:225], off
	v_lshl_add_u64 v[224:225], s[50:51], 0, v[168:169]
	s_add_i32 m0, s47, 0x2000
	s_nop 0
	global_load_lds_dwordx4 v[224:225], off
	v_lshl_add_u64 v[224:225], v[228:229], 0, s[16:17]
	s_mov_b32 m0, s65
	s_nop 0
	global_load_lds_dwordx4 v[224:225], off
	v_lshl_add_u64 v[224:225], v[230:231], 0, s[16:17]
	s_mov_b32 m0, s66
	s_nop 0
	global_load_lds_dwordx4 v[224:225], off
	s_waitcnt vmcnt(8)
	s_waitcnt lgkmcnt(0)
	s_barrier
	s_setprio 1
	s_waitcnt lgkmcnt(0)
	v_mfma_f32_16x16x32_bf16 v[62:65], v[130:133], v[180:183], v[62:65]
	v_mfma_f32_16x16x32_bf16 v[58:61], v[138:141], v[180:183], v[58:61]
	v_mfma_f32_16x16x32_bf16 v[54:57], v[130:133], v[188:191], v[54:57]
	v_mfma_f32_16x16x32_bf16 v[50:53], v[138:141], v[188:191], v[50:53]
	v_mfma_f32_16x16x32_bf16 v[38:41], v[130:133], v[196:199], v[38:41]
	v_mfma_f32_16x16x32_bf16 v[34:37], v[138:141], v[196:199], v[34:37]
	v_mfma_f32_16x16x32_bf16 v[22:25], v[130:133], v[204:207], v[22:25]
	v_mfma_f32_16x16x32_bf16 v[18:21], v[138:141], v[204:207], v[18:21]
	v_mfma_f32_16x16x32_bf16 v[62:65], v[134:137], v[184:187], v[62:65]
	v_mfma_f32_16x16x32_bf16 v[58:61], v[142:145], v[184:187], v[58:61]
	v_mfma_f32_16x16x32_bf16 v[54:57], v[134:137], v[192:195], v[54:57]
	v_mfma_f32_16x16x32_bf16 v[50:53], v[142:145], v[192:195], v[50:53]
	v_mfma_f32_16x16x32_bf16 v[38:41], v[134:137], v[200:203], v[38:41]
	v_mfma_f32_16x16x32_bf16 v[34:37], v[142:145], v[200:203], v[34:37]
	v_mfma_f32_16x16x32_bf16 v[22:25], v[134:137], v[220:223], v[22:25]
	v_mfma_f32_16x16x32_bf16 v[18:21], v[142:145], v[220:223], v[18:21]
	s_setprio 0
	s_setprio 1
	v_mfma_f32_16x16x32_bf16 v[46:49], v[146:149], v[180:183], v[46:49]
	v_mfma_f32_16x16x32_bf16 v[42:45], v[154:157], v[180:183], v[42:45]
	v_mfma_f32_16x16x32_bf16 v[30:33], v[146:149], v[188:191], v[30:33]
	v_mfma_f32_16x16x32_bf16 v[26:29], v[154:157], v[188:191], v[26:29]
	v_mfma_f32_16x16x32_bf16 v[14:17], v[146:149], v[196:199], v[14:17]
	v_mfma_f32_16x16x32_bf16 v[10:13], v[154:157], v[196:199], v[10:13]
	v_mfma_f32_16x16x32_bf16 v[6:9], v[146:149], v[204:207], v[6:9]
	v_mfma_f32_16x16x32_bf16 v[2:5], v[154:157], v[204:207], v[2:5]
	v_mfma_f32_16x16x32_bf16 v[46:49], v[150:153], v[184:187], v[46:49]
	v_mfma_f32_16x16x32_bf16 v[42:45], v[158:161], v[184:187], v[42:45]
	v_mfma_f32_16x16x32_bf16 v[30:33], v[150:153], v[192:195], v[30:33]
	v_mfma_f32_16x16x32_bf16 v[26:29], v[158:161], v[192:195], v[26:29]
	v_mfma_f32_16x16x32_bf16 v[14:17], v[150:153], v[200:203], v[14:17]
	v_mfma_f32_16x16x32_bf16 v[10:13], v[158:161], v[200:203], v[10:13]
	v_mfma_f32_16x16x32_bf16 v[6:9], v[150:153], v[220:223], v[6:9]
	v_mfma_f32_16x16x32_bf16 v[2:5], v[158:161], v[220:223], v[2:5]
	s_setprio 0
	s_barrier
	s_add_u32 s37, s37, 0x100
	s_addc_u32 s39, s39, 0
	s_mov_b64 s[50:51], s[52:53]
	s_mov_b32 s47, s49
